# v32: v31 + phase-10 combine: next batch's slot-map/affinity words loaded one iteration ahead (gathers start without the first round trip)
# speedup vs baseline: 1.0160x; 1.0004x over previous
.LBB0_1091:
	s_ashr_i32 s41, s40, 31
	s_lshl_b64 s[42:43], s[40:41], 11
	v_lshl_add_u64 v[124:125], v[100:101], 0, s[42:43]
	global_load_dwordx4 v[76:79], v[124:125], off
	global_load_dwordx4 v[72:75], v[124:125], off offset:1024
	global_load_dwordx4 v[68:71], v[124:125], off offset:2048
	global_load_dwordx4 v[64:67], v[124:125], off offset:3072
	s_lshl_b64 s[14:15], s[40:41], 6
	s_waitcnt lgkmcnt(0)
	v_lshl_add_u64 v[48:49], s[40:41], 2, v[92:93]
	v_lshl_add_u64 v[50:51], v[90:91], 0, s[14:15]
	v_add_co_u32_e32 v104, vcc, 0x1000, v124
	s_nop 1
	v_addc_co_u32_e32 v105, vcc, 0, v125, vcc
	s_cmp_eq_u32 s44, 0
	s_cbranch_scc1 .Lcp_first10
	v_mov_b32_e32 v168, v200
	v_mov_b32_e32 v169, v201
	s_branch .Lcp_go10
.Lcp_first10:
	global_load_dword v168, v[48:49], off
	global_load_dword v169, v[50:51], off
	s_waitcnt vmcnt(0)
.Lcp_go10:
	global_load_dword v200, v[48:49], off offset:16
	global_load_dword v201, v[50:51], off offset:256
	global_load_dwordx4 v[60:63], v[104:105], off
	global_load_dwordx4 v[56:59], v[104:105], off offset:1024
	global_load_dwordx4 v[52:55], v[104:105], off offset:2048
	s_nop 0
	global_load_dwordx4 v[48:51], v[104:105], off offset:3072
	v_cmp_lt_i32_e64 s[14:15], -1, v168
	s_and_b32 s52, s14, 0xffff
	s_cmp_eq_u32 s52, 0
	s_cbranch_scc1 .LBB0_1096
	v_mov_b32_e32 v112, 0
	v_mov_b32_e32 v113, v112
	v_mov_b32_e32 v104, v112
	v_mov_b32_e32 v105, v112
	v_mov_b32_e32 v108, v112
	v_mov_b32_e32 v109, v112
	v_mov_b32_e32 v110, v112
	v_mov_b32_e32 v111, v112
	v_mov_b32_e32 v114, v112
	v_mov_b32_e32 v115, v112
	v_mov_b32_e32 v106, v112
	v_mov_b32_e32 v107, v112
	v_mov_b32_e32 v118, v112
	v_mov_b32_e32 v119, v112
	v_mov_b32_e32 v116, v112
	v_mov_b32_e32 v117, v112
	s_branch .LBB0_1094

.LBB0_1096:
	s_waitcnt vmcnt(6)
	v_mov_b32_e32 v117, 0
	v_mov_b32_e32 v116, v117
	v_mov_b32_e32 v119, v117
	v_mov_b32_e32 v118, v117
	v_mov_b32_e32 v107, v117
	v_mov_b32_e32 v106, v117
	v_mov_b32_e32 v115, v117
	v_mov_b32_e32 v114, v117
	v_mov_b32_e32 v111, v117
	v_mov_b32_e32 v110, v117
	v_mov_b32_e32 v109, v117
	v_mov_b32_e32 v108, v117
	v_mov_b32_e32 v105, v117
	v_mov_b32_e32 v104, v117
	v_mov_b32_e32 v113, v117
	v_mov_b32_e32 v112, v117
